# hgrn_b1: all 48 global loads of a chunk item issued up front (one round trip instead of ~8), G stores after
# speedup vs baseline: 1.0250x; 1.0126x over previous
.LBB0_1359:
	v_mov_b32_e32 v24, v220
	s_ashr_i32 s6, s35, 8
	s_ashr_i32 s7, s6, 31
	v_ashrrev_i32_e32 v11, 7, v24
	s_lshl_b64 s[6:7], s[6:7], 12
	s_and_b32 s8, s17, 0xfc0
	v_lshlrev_b32_e32 v0, 4, v11
	s_or_b32 s6, s6, s8
	v_ashrrev_i32_e32 v1, 31, v0
	v_lshl_add_u64 v[0:1], s[6:7], 0, v[0:1]
	v_lshlrev_b64 v[2:3], 11, v[0:1]
	s_and_b32 s22, s1, 0x180
	v_and_b32_e32 v10, 0x7f, v24
	v_lshl_add_u64 v[2:3], s[14:15], 0, v[2:3]
	s_lshl_b32 s48, s22, 2
	v_lshl_add_u64 v[2:3], v[2:3], 0, s[48:49]
	v_lshlrev_b32_e32 v96, 2, v10
	v_lshl_add_u64 v[22:23], v[2:3], 0, v[96:97]
	v_lshlrev_b64 v[0:1], 10, v[0:1]
	v_lshl_add_u64 v[4:5], s[24:25], 0, v[0:1]
	s_lshl_b32 s48, s22, 1
	v_lshl_add_u64 v[0:1], s[30:31], 0, v[0:1]
	v_lshl_add_u64 v[4:5], v[4:5], 0, s[48:49]
	v_lshlrev_b32_e32 v8, 1, v10
	v_mov_b32_e32 v9, v97
	v_lshl_add_u64 v[0:1], v[0:1], 0, s[48:49]
	v_add_u32_e32 v43, 0, v96
	v_lshl_add_u64 v[4:5], v[4:5], 0, v[8:9]
	v_lshl_add_u64 v[8:9], v[0:1], 0, v[8:9]
	v_mul_u32_u24_e32 v0, 0x8c, v10
	v_lshlrev_b32_e32 v1, 5, v11
	v_add3_u32 v25, v43, v0, v1
	v_lshl_add_u32 v42, v24, 2, 0
	v_readfirstlane_b32 s40, v24
	v_add_co_u32_e32 v12, vcc, 0x2000, v22
	s_nop 1
	v_addc_co_u32_e32 v13, vcc, 0, v23, vcc
	v_add_co_u32_e32 v14, vcc, 0x4000, v22
	s_nop 1
	v_addc_co_u32_e32 v15, vcc, 0, v23, vcc
	v_add_co_u32_e32 v16, vcc, 0x6000, v22
	s_nop 1
	v_addc_co_u32_e32 v17, vcc, 0, v23, vcc
	v_add_co_u32_e32 v18, vcc, 0x7000, v22
	s_nop 1
	v_addc_co_u32_e32 v19, vcc, 0, v23, vcc
	v_lshl_add_u64 v[26:27], s[62:63], 4, v[4:5]
	v_lshl_add_u64 v[28:29], s[62:63], 4, v[26:27]
	v_lshl_add_u64 v[30:31], s[62:63], 4, v[28:29]
	v_lshl_add_u64 v[32:33], s[62:63], 4, v[8:9]
	v_lshl_add_u64 v[34:35], s[62:63], 4, v[32:33]
	v_lshl_add_u64 v[36:37], s[62:63], 4, v[34:35]
	global_load_dword v100, v[22:23], off
	global_load_dword v101, v[22:23], off offset:2048
	global_load_dword v102, v[12:13], off offset:-4096
	global_load_dword v103, v[12:13], off offset:-2048
	global_load_dword v104, v[12:13], off
	global_load_dword v105, v[12:13], off offset:2048
	global_load_dword v106, v[14:15], off offset:-4096
	global_load_dword v107, v[14:15], off offset:-2048
	global_load_dword v108, v[14:15], off
	global_load_dword v109, v[14:15], off offset:2048
	global_load_dword v110, v[16:17], off offset:-4096
	global_load_dword v111, v[16:17], off offset:-2048
	global_load_dword v112, v[16:17], off
	global_load_dword v113, v[16:17], off offset:2048
	global_load_dword v114, v[18:19], off
	global_load_dword v115, v[18:19], off offset:2048
	global_load_ushort v116, v[4:5], off
	global_load_ushort v117, v[4:5], off offset:1024
	global_load_ushort v118, v[4:5], off offset:2048
	global_load_ushort v119, v[4:5], off offset:3072
	global_load_ushort v120, v[26:27], off
	global_load_ushort v121, v[26:27], off offset:1024
	global_load_ushort v122, v[26:27], off offset:2048
	global_load_ushort v123, v[26:27], off offset:3072
	global_load_ushort v124, v[28:29], off
	global_load_ushort v125, v[28:29], off offset:1024
	global_load_ushort v126, v[28:29], off offset:2048
	global_load_ushort v127, v[28:29], off offset:3072
	global_load_ushort v128, v[30:31], off
	global_load_ushort v129, v[30:31], off offset:1024
	global_load_ushort v130, v[30:31], off offset:2048
	global_load_ushort v131, v[30:31], off offset:3072
	global_load_ushort v132, v[8:9], off
	global_load_ushort v133, v[8:9], off offset:1024
	global_load_ushort v134, v[8:9], off offset:2048
	global_load_ushort v135, v[8:9], off offset:3072
	global_load_ushort v136, v[32:33], off
	global_load_ushort v137, v[32:33], off offset:1024
	global_load_ushort v138, v[32:33], off offset:2048
	global_load_ushort v139, v[32:33], off offset:3072
	global_load_ushort v140, v[34:35], off
	global_load_ushort v141, v[34:35], off offset:1024
	global_load_ushort v142, v[34:35], off offset:2048
	global_load_ushort v143, v[34:35], off offset:3072
	global_load_ushort v144, v[36:37], off
	global_load_ushort v145, v[36:37], off offset:1024
	global_load_ushort v146, v[36:37], off offset:2048
	global_load_ushort v147, v[36:37], off offset:3072
	s_waitcnt vmcnt(32)
	v_add_f32_e32 v100, 0, v100
	v_add_f32_e32 v101, v100, v101
	v_add_f32_e32 v102, v101, v102
	v_add_f32_e32 v103, v102, v103
	v_add_f32_e32 v104, v103, v104
	v_add_f32_e32 v105, v104, v105
	v_add_f32_e32 v106, v105, v106
	v_add_f32_e32 v107, v106, v107
	v_add_f32_e32 v108, v107, v108
	v_add_f32_e32 v109, v108, v109
	v_add_f32_e32 v110, v109, v110
	v_add_f32_e32 v111, v110, v111
	v_add_f32_e32 v112, v111, v112
	v_add_f32_e32 v113, v112, v113
	v_add_f32_e32 v114, v113, v114
	v_add_f32_e32 v115, v114, v115
	ds_write_b32 v42, v115
	s_waitcnt lgkmcnt(0)
	s_barrier
	ds_read2st64_b32 v[48:49], v43 offset1:2
	ds_read2st64_b32 v[50:51], v43 offset0:4 offset1:6
	v_cmp_lt_i32_e64 s[10:11], 0, v11
	v_cmp_lt_i32_e64 s[8:9], 1, v11
	v_cmp_lt_i32_e64 s[6:7], 2, v11
	s_waitcnt lgkmcnt(0)
	v_add_f32_e32 v0, 0, v48
	v_cndmask_b32_e64 v1, 0, v0, s[10:11]
	v_add_f32_e32 v2, v49, v1
	v_cndmask_b32_e64 v1, v1, v2, s[8:9]
	v_add_f32_e32 v0, v0, v49
	v_add_f32_e32 v2, v50, v1
	v_cndmask_b32_e64 v1, v1, v2, s[6:7]
	v_add_f32_e32 v0, v0, v50
	v_add_f32_e32 v0, v0, v51
	v_add_f32_e32 v100, v100, v1
	v_add_f32_e32 v101, v101, v1
	v_add_f32_e32 v102, v102, v1
	v_add_f32_e32 v103, v103, v1
	v_add_f32_e32 v104, v104, v1
	v_add_f32_e32 v105, v105, v1
	v_add_f32_e32 v106, v106, v1
	v_add_f32_e32 v107, v107, v1
	v_add_f32_e32 v108, v108, v1
	v_add_f32_e32 v109, v109, v1
	v_add_f32_e32 v110, v110, v1
	v_add_f32_e32 v111, v111, v1
	v_add_f32_e32 v112, v112, v1
	v_add_f32_e32 v113, v113, v1
	v_add_f32_e32 v114, v114, v1
	v_add_f32_e32 v115, v115, v1
	v_sub_f32_e32 v52, v0, v100
	v_sub_f32_e32 v53, v0, v101
	v_sub_f32_e32 v54, v0, v102
	v_sub_f32_e32 v55, v0, v103
	v_sub_f32_e32 v56, v0, v104
	v_sub_f32_e32 v57, v0, v105
	v_sub_f32_e32 v58, v0, v106
	v_sub_f32_e32 v59, v0, v107
	v_sub_f32_e32 v60, v0, v108
	v_sub_f32_e32 v61, v0, v109
	v_sub_f32_e32 v62, v0, v110
	v_sub_f32_e32 v63, v0, v111
	v_sub_f32_e32 v64, v0, v112
	v_sub_f32_e32 v65, v0, v113
	v_sub_f32_e32 v66, v0, v114
	v_sub_f32_e32 v67, v0, v115
	v_mul_f32_e32 v52, 0x3fb8aa3b, v52
	v_mul_f32_e32 v53, 0x3fb8aa3b, v53
	v_mul_f32_e32 v54, 0x3fb8aa3b, v54
	v_mul_f32_e32 v55, 0x3fb8aa3b, v55
	v_mul_f32_e32 v56, 0x3fb8aa3b, v56
	v_mul_f32_e32 v57, 0x3fb8aa3b, v57
	v_mul_f32_e32 v58, 0x3fb8aa3b, v58
	v_mul_f32_e32 v59, 0x3fb8aa3b, v59
	v_mul_f32_e32 v60, 0x3fb8aa3b, v60
	v_mul_f32_e32 v61, 0x3fb8aa3b, v61
	v_mul_f32_e32 v62, 0x3fb8aa3b, v62
	v_mul_f32_e32 v63, 0x3fb8aa3b, v63
	v_mul_f32_e32 v64, 0x3fb8aa3b, v64
	v_mul_f32_e32 v65, 0x3fb8aa3b, v65
	v_mul_f32_e32 v66, 0x3fb8aa3b, v66
	v_mul_f32_e32 v67, 0x3fb8aa3b, v67
	v_exp_f32_e32 v52, v52
	v_exp_f32_e32 v53, v53
	v_exp_f32_e32 v54, v54
	v_exp_f32_e32 v55, v55
	v_exp_f32_e32 v56, v56
	v_exp_f32_e32 v57, v57
	v_exp_f32_e32 v58, v58
	v_exp_f32_e32 v59, v59
	v_exp_f32_e32 v60, v60
	v_exp_f32_e32 v61, v61
	v_exp_f32_e32 v62, v62
	v_exp_f32_e32 v63, v63
	v_exp_f32_e32 v64, v64
	v_exp_f32_e32 v65, v65
	v_exp_f32_e32 v66, v66
	v_exp_f32_e32 v67, v67
	global_store_dword v[22:23], v100, off
	global_store_dword v[22:23], v101, off offset:2048
	global_store_dword v[12:13], v102, off offset:-4096
	global_store_dword v[12:13], v103, off offset:-2048
	global_store_dword v[12:13], v104, off
	global_store_dword v[12:13], v105, off offset:2048
	global_store_dword v[14:15], v106, off offset:-4096
	global_store_dword v[14:15], v107, off offset:-2048
	global_store_dword v[14:15], v108, off
	global_store_dword v[14:15], v109, off offset:2048
	global_store_dword v[16:17], v110, off offset:-4096
	global_store_dword v[16:17], v111, off offset:-2048
	global_store_dword v[16:17], v112, off
	global_store_dword v[16:17], v113, off offset:2048
	global_store_dword v[18:19], v114, off
	global_store_dword v[18:19], v115, off offset:2048
	s_waitcnt vmcnt(16)
	v_lshlrev_b32_e32 v116, 16, v116
	v_lshlrev_b32_e32 v117, 16, v117
	v_lshlrev_b32_e32 v118, 16, v118
	v_lshlrev_b32_e32 v119, 16, v119
	v_lshlrev_b32_e32 v120, 16, v120
	v_lshlrev_b32_e32 v121, 16, v121
	v_lshlrev_b32_e32 v122, 16, v122
	v_lshlrev_b32_e32 v123, 16, v123
	v_lshlrev_b32_e32 v124, 16, v124
	v_lshlrev_b32_e32 v125, 16, v125
	v_lshlrev_b32_e32 v126, 16, v126
	v_lshlrev_b32_e32 v127, 16, v127
	v_lshlrev_b32_e32 v128, 16, v128
	v_lshlrev_b32_e32 v129, 16, v129
	v_lshlrev_b32_e32 v130, 16, v130
	v_lshlrev_b32_e32 v131, 16, v131
	v_mul_f32_e32 v52, v52, v116
	v_mul_f32_e32 v53, v53, v117
	v_mul_f32_e32 v54, v54, v118
	v_mul_f32_e32 v55, v55, v119
	v_mul_f32_e32 v56, v56, v120
	v_mul_f32_e32 v57, v57, v121
	v_mul_f32_e32 v58, v58, v122
	v_mul_f32_e32 v59, v59, v123
	v_mul_f32_e32 v60, v60, v124
	v_mul_f32_e32 v61, v61, v125
	v_mul_f32_e32 v62, v62, v126
	v_mul_f32_e32 v63, v63, v127
	v_mul_f32_e32 v64, v64, v128
	v_mul_f32_e32 v65, v65, v129
	v_mul_f32_e32 v66, v66, v130
	v_mul_f32_e32 v67, v67, v131
	v_cvt_pk_bf16_f32 v68, v52, v53
	v_cvt_pk_bf16_f32 v69, v54, v55
	v_cvt_pk_bf16_f32 v70, v56, v57
	v_cvt_pk_bf16_f32 v71, v58, v59
	v_cvt_pk_bf16_f32 v72, v60, v61
	v_cvt_pk_bf16_f32 v73, v62, v63
	v_cvt_pk_bf16_f32 v74, v64, v65
	v_cvt_pk_bf16_f32 v75, v66, v67
	ds_write_b128 v25, v[68:71] offset:2048
	ds_write_b128 v25, v[72:75] offset:2064
	v_perm_b32 v76, v133, v132, s47
	v_perm_b32 v77, v135, v134, s47
	v_perm_b32 v78, v137, v136, s47
	v_perm_b32 v79, v139, v138, s47
	v_perm_b32 v80, v141, v140, s47
	v_perm_b32 v81, v143, v142, s47
	v_perm_b32 v82, v145, v144, s47
	v_perm_b32 v83, v147, v146, s47
	ds_write_b128 v25, v[76:79] offset:20480
	ds_write_b128 v25, v[80:83] offset:20496
	v_cmp_gt_u32_e32 vcc, 0x80, v24
	s_and_saveexec_b64 s[6:7], vcc
	s_cbranch_execz .LBB0_1358
	v_mul_f32_e32 v0, 0x3fb8aa3b, v0
	v_exp_f32_e32 v0, v0
	global_store_dword v96, v0, s[52:53]
	s_branch .LBB0_1358
